# moba static pairing refined from per-class idle time at barrier 5: scan+prep class one step lighter (0,11)/(1,10), prep-only class one step heavier (9,6)/(8,7), the one prep-only workgroup that also r
# baseline (speedup 1.0000x reference)
.LBB0_565:
	s_cbranch_execz .LBB0_643
	s_lshl_b32 s0, s76, 2
	s_and_b32 s73, s0, 28
	s_lshl_b32 s0, s76, 11
	s_ashr_i32 s33, s76, 3
	s_lshr_b32 s98, s33, 3
	s_lshl_b32 s98, s98, 2
	s_lshr_b32 s98, 0xcdef8910, s98
	s_and_b32 s98, s98, 15
	s_cmpk_eq_u32 s76, 0x80
	s_cselect_b32 s98, 7, s98
	s_sub_i32 s98, 15, s98
	s_lshl_b32 s98, s98, 3
	s_and_b32 s33, s33, 7
	s_or_b32 s33, s33, s98
	s_and_b32 s52, s0, 0x3000
	s_ashr_i32 s2, s42, 3
	s_not_b32 s72, s33
	s_or_b32 s74, s52, 64
	s_add_u32 s66, s58, 0x2cd1000
	s_addc_u32 s67, s59, 0
	s_add_u32 s75, s58, 0x8cd1000
	s_addc_u32 s77, s59, 0
	s_add_u32 s78, s58, 0xbd0000
	v_mbcnt_lo_u32_b32 v0, -1, 0
	s_addc_u32 s79, s59, 0
	v_mbcnt_hi_u32_b32 v196, -1, v0
	s_mov_b32 s63, 0
	s_add_u32 s68, s58, 0xcd1000
	v_and_b32_e32 v0, 64, v196
	s_mov_b32 s53, s63
	s_addc_u32 s69, s59, 0
	v_mov_b32_e32 v33, 0
	s_movk_i32 s80, 0xff
	s_movk_i32 s81, 0x1800
	s_mov_b32 s82, 0xefa18f08
	v_xor_b32_e32 v197, 32, v196
	v_add_u32_e32 v198, 64, v0
	v_mov_b32_e32 v199, 0xff800000
	v_mov_b32_e32 v200, 0x3f803f80
	s_mov_b32 s6, 0
	s_mov_b32 s83, 0
	v_readlane_b32 s98, v255, 14
	s_nop 3
	s_cmp_lg_u32 s98, 0
	s_cbranch_scc1 .Lmoba_dq_latch2
	s_branch .LBB0_569

.Lmoba_dq_latch2:
	s_waitcnt lgkmcnt(0)
	s_barrier
	v_readlane_b32 s98, v255, 19
	s_nop 3
	s_cmp_lg_u32 s98, 0
	s_cbranch_scc1 .LBB0_643
	s_mov_b32 s98, 1
	s_nop 0
	v_writelane_b32 v255, s98, 19
	s_ashr_i32 s14, s76, 3
	s_lshr_b32 s0, s14, 3
	s_lshl_b32 s0, s0, 2
	s_lshr_b32 s0, 0x543276ab, s0
	s_and_b32 s0, s0, 15
	s_cmpk_eq_u32 s76, 0xc0
	s_cselect_b32 s0, 9, s0
	s_sub_i32 s0, 15, s0
	s_lshl_b32 s0, s0, 3
	s_and_b32 s14, s14, 7
	s_or_b32 s14, s14, s0
	s_branch .LBB0_574
